# S5 pass 1: chunk weighted sums via packed f32 FMAs over time-slot pairs (64 packed ops instead of 128 scalar per chunk), weights re-laid out into aligned pairs once per phase
# baseline (speedup 1.0000x reference)
.LBB0_895:
	s_andn2_b64 vcc, exec, s[4:5]
	s_cbranch_vccnz .LBB0_925
	v_readlane_b32 s4, v254, 28
	v_readlane_b32 s5, v254, 29
	s_mov_b32 s5, s29
	s_lshl_b64 s[2:3], s[4:5], 16
	s_waitcnt lgkmcnt(0)
	s_add_u32 s2, s82, s2
	s_addc_u32 s3, s83, s3
	s_add_u32 s8, s2, 0x8340000
	s_addc_u32 s9, s3, 0
	v_mov_b32_e32 v126, v247
	s_lshl_b64 s[6:7], s[4:5], 19
	s_add_u32 s2, s82, s6
	v_bfe_u32 v127, v126, 5, 1
	v_readfirstlane_b32 s10, v126
	s_addc_u32 s3, s83, s7
	v_lshlrev_b32_e32 v208, 4, v127
	s_mov_b32 s20, s4
	s_ashr_i32 s4, s10, 8
	v_lshl_add_u64 v[0:1], s[2:3], 0, v[208:209]
	v_readlane_b32 s2, v253, 61
	s_add_i32 s4, s2, s4
	s_and_b32 s13, s4, 0x7f
	s_waitcnt vmcnt(0)
	v_and_b32_e32 v134, 31, v126
	s_lshl_b32 s14, s13, 7
	v_or_b32_e32 v2, s14, v134
	v_and_b32_e32 v128, 63, v126
	s_lshl_b32 s2, s13, 9
	v_lshlrev_b32_e32 v2, 5, v2
	v_mov_b32_e32 v3, v209
	v_lshl_or_b32 v4, v128, 3, s2
	v_lshl_add_u64 v[0:1], v[0:1], 0, v[2:3]
	s_mov_b64 s[2:3], 0x8360000
	v_lshl_add_u64 v[2:3], v[0:1], 0, s[2:3]
	v_add_co_u32_e32 v0, vcc, 0x8360000, v0
	s_ashr_i32 s11, s10, 6
	s_nop 0
	v_addc_co_u32_e32 v1, vcc, 0, v1, vcc
	global_load_dwordx4 v[64:67], v[0:1], off
	global_load_dwordx2 v[124:125], v4, s[8:9]
	global_load_dwordx4 v[68:71], v[2:3], off offset:1024
	global_load_dwordx4 v[72:75], v[2:3], off offset:2048
	global_load_dwordx4 v[76:79], v[2:3], off offset:3072
	s_ashr_i32 s2, s4, 7
	s_and_b32 s12, s11, 3
	s_ashr_i32 s3, s2, 31
	s_lshl_b64 s[2:3], s[2:3], 23
	s_lshl_b32 s4, s12, 21
	s_or_b32 s4, s2, s4
	s_add_u32 s4, s82, s4
	s_addc_u32 s5, s83, s3
	s_lshl_b32 s15, s13, 5
	s_add_u32 s4, s4, s15
	s_addc_u32 s5, s5, 0
	s_add_u32 s4, s4, 0xa800000
	v_lshlrev_b32_e32 v0, 3, v127
	s_addc_u32 s5, s5, 0
	v_lshlrev_b32_e32 v132, 11, v134
	v_and_b32_e32 v2, 32, v126
	s_cmp_eq_u32 s12, 3
	v_mov_b32_e32 v1, 0
	v_lshlrev_b32_e32 v122, 1, v132
	v_lshlrev_b32_e32 v120, 1, v0
	v_lshrrev_b32_e32 v135, 1, v2
	v_mov_b32_e32 v0, 0
	s_mul_i32 s100, s11, 0x4200
	v_add_u32_e32 v174, v122, v120
	v_lshl_add_u32 v175, v128, 4, s100
	v_lshlrev_b32_e32 v176, 4, v134
	v_lshl_add_u32 v176, v127, 3, v176
	v_add_u32_e32 v176, s100, v176
	s_cbranch_scc1 .LBB0_900
	v_lshlrev_b32_e32 v0, 3, v134
	v_mov_b32_e32 v1, v209
	v_lshl_add_u64 v[0:1], s[8:9], 0, v[0:1]
	s_lshl_b32 s28, s14, 2
	v_lshl_add_u64 v[0:1], v[0:1], 0, s[28:29]
	global_load_dwordx2 v[2:3], v[0:1], off
	v_cmp_gt_u32_e32 vcc, 32, v128
	global_load_dwordx2 v[0:1], v[0:1], off offset:256
	v_mov_b32_e32 v123, v209
	v_mov_b32_e32 v121, v209
	s_lshl_b32 s9, s10, 15
	s_and_b32 s9, s9, 0x600000
	s_or_b32 s9, s2, s9
	s_lshr_b32 s8, s10, 8
	v_mov_b32_e32 v84, 0
	v_mov_b32_e32 v94, v84
	v_mov_b32_e32 v95, v84
	s_waitcnt vmcnt(1)
	v_fmamk_f32 v4, v3, 0x80000000, v2
	v_fma_f32 v5, 0, v2, v3
	v_mul_f32_e32 v6, v3, v4
	v_mul_f32_e32 v7, v3, v5
	v_fmac_f32_e32 v6, v2, v5
	v_fma_f32 v7, v2, v4, -v7
	v_mul_f32_e32 v9, v2, v6
	v_mul_f32_e32 v8, v3, v6
	v_fmac_f32_e32 v9, v3, v7
	v_fma_f32 v11, v2, v7, -v8
	v_mul_f32_e32 v8, v2, v9
	v_mul_f32_e32 v10, v3, v9
	v_fmac_f32_e32 v8, v3, v11
	v_fma_f32 v10, v2, v11, -v10
	v_mul_f32_e32 v12, v2, v8
	v_mul_f32_e32 v13, v3, v8
	v_fmac_f32_e32 v12, v3, v10
	v_fma_f32 v13, v2, v10, -v13
	v_mul_f32_e32 v14, v2, v12
	v_mul_f32_e32 v15, v3, v12
	v_fmac_f32_e32 v14, v3, v13
	v_fma_f32 v15, v2, v13, -v15
	v_mul_f32_e32 v16, v2, v14
	v_mul_f32_e32 v17, v3, v14
	v_fmac_f32_e32 v16, v3, v15
	v_fma_f32 v17, v2, v15, -v17
	v_mul_f32_e32 v18, v2, v16
	v_mul_f32_e32 v19, v3, v16
	v_fmac_f32_e32 v18, v3, v17
	v_fma_f32 v19, v2, v17, -v19
	v_mul_f32_e32 v20, v2, v18
	v_mul_f32_e32 v21, v3, v18
	v_fmac_f32_e32 v20, v3, v19
	v_fma_f32 v21, v2, v19, -v21
	v_mul_f32_e32 v22, v2, v20
	v_mul_f32_e32 v23, v3, v20
	v_fmac_f32_e32 v22, v3, v21
	v_fma_f32 v23, v2, v21, -v23
	v_mul_f32_e32 v25, v2, v22
	v_mul_f32_e32 v24, v3, v22
	v_fmac_f32_e32 v25, v3, v23
	v_fma_f32 v27, v2, v23, -v24
	v_mul_f32_e32 v24, v2, v25
	v_mul_f32_e32 v26, v3, v25
	v_fmac_f32_e32 v24, v3, v27
	v_fma_f32 v26, v2, v27, -v26
	v_mul_f32_e32 v28, v2, v24
	v_mul_f32_e32 v29, v3, v24
	v_fmac_f32_e32 v28, v3, v26
	v_fma_f32 v29, v2, v26, -v29
	v_mul_f32_e32 v30, v2, v28
	v_mul_f32_e32 v31, v3, v28
	v_fmac_f32_e32 v30, v3, v29
	v_fma_f32 v31, v2, v29, -v31
	v_mul_f32_e32 v32, v2, v30
	v_mul_f32_e32 v33, v3, v30
	v_fmac_f32_e32 v32, v3, v31
	v_fma_f32 v33, v2, v31, -v33
	v_mul_f32_e32 v34, v2, v32
	v_mul_f32_e32 v35, v3, v32
	v_fmac_f32_e32 v34, v3, v33
	v_fma_f32 v35, v2, v33, -v35
	v_mul_f32_e32 v36, v2, v34
	v_mul_f32_e32 v37, v3, v34
	v_fmac_f32_e32 v36, v3, v35
	v_fma_f32 v37, v2, v35, -v37
	v_mul_f32_e32 v38, v2, v36
	v_mul_f32_e32 v39, v3, v36
	v_fmac_f32_e32 v38, v3, v37
	v_fma_f32 v39, v2, v37, -v39
	v_mul_f32_e32 v46, v2, v38
	v_mul_f32_e32 v40, v3, v38
	v_fmac_f32_e32 v46, v3, v39
	v_fma_f32 v47, v2, v39, -v40
	v_mul_f32_e32 v40, v2, v46
	v_mul_f32_e32 v41, v3, v46
	v_fmac_f32_e32 v40, v3, v47
	v_fma_f32 v41, v2, v47, -v41
	v_mul_f32_e32 v42, v2, v40
	v_mul_f32_e32 v43, v3, v40
	v_fmac_f32_e32 v42, v3, v41
	v_fma_f32 v43, v2, v41, -v43
	v_mul_f32_e32 v44, v2, v42
	v_mul_f32_e32 v45, v3, v42
	v_fmac_f32_e32 v44, v3, v43
	v_fma_f32 v45, v2, v43, -v45
	v_mul_f32_e32 v49, v2, v44
	v_mul_f32_e32 v48, v3, v44
	v_fmac_f32_e32 v49, v3, v45
	v_fma_f32 v48, v2, v45, -v48
	v_mul_f32_e32 v51, v2, v49
	v_mul_f32_e32 v50, v3, v49
	v_fmac_f32_e32 v51, v3, v48
	v_fma_f32 v50, v2, v48, -v50
	v_mul_f32_e32 v53, v2, v51
	v_mul_f32_e32 v52, v3, v51
	v_fmac_f32_e32 v53, v3, v50
	v_fma_f32 v52, v2, v50, -v52
	v_mul_f32_e32 v55, v2, v53
	v_mul_f32_e32 v54, v3, v53
	v_fmac_f32_e32 v55, v3, v52
	v_fma_f32 v54, v2, v52, -v54
	v_mul_f32_e32 v57, v2, v55
	v_mul_f32_e32 v56, v3, v55
	v_fmac_f32_e32 v57, v3, v54
	v_fma_f32 v56, v2, v54, -v56
	v_mul_f32_e32 v59, v2, v57
	v_mul_f32_e32 v58, v3, v57
	v_fmac_f32_e32 v59, v3, v56
	v_fma_f32 v58, v2, v56, -v58
	v_mul_f32_e32 v61, v2, v59
	v_mul_f32_e32 v60, v3, v59
	v_fmac_f32_e32 v61, v3, v58
	v_fma_f32 v60, v2, v58, -v60
	v_mul_f32_e32 v63, v2, v61
	v_mul_f32_e32 v62, v3, v61
	v_fmac_f32_e32 v63, v3, v60
	v_fma_f32 v62, v2, v60, -v62
	v_mul_f32_e32 v81, v2, v63
	v_mul_f32_e32 v80, v3, v63
	v_fmac_f32_e32 v81, v3, v62
	v_cndmask_b32_e32 v108, v4, v13, vcc
	s_waitcnt vmcnt(0)
	v_fmamk_f32 v4, v1, 0x80000000, v0
	v_fma_f32 v80, v2, v62, -v80
	v_mul_f32_e32 v82, v3, v81
	v_cndmask_b32_e32 v110, v7, v15, vcc
	v_cndmask_b32_e32 v109, v5, v12, vcc
	v_fma_f32 v5, 0, v0, v1
	v_mul_f32_e32 v7, v1, v4
	v_mul_f32_e32 v86, v2, v81
	v_fma_f32 v88, v2, v80, -v82
	v_mul_f32_e32 v2, v1, v5
	v_fmac_f32_e32 v7, v0, v5
	v_cndmask_b32_e32 v113, v9, v16, vcc
	v_cndmask_b32_e32 v111, v6, v14, vcc
	v_fma_f32 v6, v0, v4, -v2
	v_mul_f32_e32 v9, v0, v7
	v_mul_f32_e32 v2, v1, v7
	v_fmac_f32_e32 v9, v1, v6
	v_cndmask_b32_e32 v112, v11, v17, vcc
	v_cndmask_b32_e32 v107, 0, v8, vcc
	v_fma_f32 v8, v0, v6, -v2
	v_mul_f32_e32 v11, v0, v9
	v_mul_f32_e32 v2, v1, v9
	v_fmac_f32_e32 v11, v1, v8
	v_cndmask_b32_e32 v106, 1.0, v10, vcc
	v_fma_f32 v10, v0, v8, -v2
	v_mul_f32_e32 v13, v0, v11
	v_mul_f32_e32 v2, v1, v11
	v_fmac_f32_e32 v13, v1, v10
	v_fma_f32 v12, v0, v10, -v2
	v_mul_f32_e32 v15, v0, v13
	v_mul_f32_e32 v2, v1, v13
	v_fmac_f32_e32 v15, v1, v12
	v_fma_f32 v14, v0, v12, -v2
	v_mul_f32_e32 v17, v0, v15
	v_mul_f32_e32 v2, v1, v15
	v_fmac_f32_e32 v17, v1, v14
	v_cndmask_b32_e32 v114, v19, v26, vcc
	v_fma_f32 v16, v0, v14, -v2
	v_mul_f32_e32 v19, v0, v17
	v_mul_f32_e32 v2, v1, v17
	v_fmac_f32_e32 v19, v1, v16
	v_cndmask_b32_e32 v118, v21, v29, vcc
	v_cndmask_b32_e32 v116, v18, v24, vcc
	v_fma_f32 v18, v0, v16, -v2
	v_mul_f32_e32 v21, v0, v19
	v_mul_f32_e32 v2, v1, v19
	v_fmac_f32_e32 v21, v1, v18
	v_cndmask_b32_e32 v129, v23, v31, vcc
	v_cndmask_b32_e32 v119, v20, v28, vcc
	v_fma_f32 v20, v0, v18, -v2
	v_mul_f32_e32 v23, v0, v21
	v_mul_f32_e32 v2, v1, v21
	v_fmac_f32_e32 v23, v1, v20
	v_cndmask_b32_e32 v133, v25, v32, vcc
	v_cndmask_b32_e32 v130, v22, v30, vcc
	v_fma_f32 v22, v0, v20, -v2
	v_mul_f32_e32 v25, v0, v23
	v_mul_f32_e32 v2, v1, v23
	v_fmac_f32_e32 v25, v1, v22
	v_cndmask_b32_e32 v131, v27, v33, vcc
	v_fma_f32 v24, v0, v22, -v2
	v_mul_f32_e32 v27, v0, v25
	v_mul_f32_e32 v2, v1, v25
	v_fmac_f32_e32 v27, v1, v24
	v_fma_f32 v26, v0, v24, -v2
	v_mul_f32_e32 v29, v0, v27
	v_mul_f32_e32 v2, v1, v27
	v_fmac_f32_e32 v29, v1, v26
	v_fma_f32 v28, v0, v26, -v2
	v_mul_f32_e32 v31, v0, v29
	v_mul_f32_e32 v2, v1, v29
	v_fmac_f32_e32 v31, v1, v28
	v_fma_f32 v30, v0, v28, -v2
	v_mul_f32_e32 v33, v0, v31
	v_mul_f32_e32 v2, v1, v31
	v_fmac_f32_e32 v33, v1, v30
	v_cndmask_b32_e32 v136, v35, v41, vcc
	v_fma_f32 v32, v0, v30, -v2
	v_mul_f32_e32 v35, v0, v33
	v_mul_f32_e32 v2, v1, v33
	v_fmac_f32_e32 v35, v1, v32
	v_cndmask_b32_e32 v138, v37, v43, vcc
	v_cndmask_b32_e32 v137, v34, v40, vcc
	v_fma_f32 v34, v0, v32, -v2
	v_mul_f32_e32 v37, v0, v35
	v_mul_f32_e32 v2, v1, v35
	v_fmac_f32_e32 v37, v1, v34
	v_cndmask_b32_e32 v140, v39, v45, vcc
	v_cndmask_b32_e32 v139, v36, v42, vcc
	v_fma_f32 v36, v0, v34, -v2
	v_mul_f32_e32 v39, v0, v37
	v_mul_f32_e32 v2, v1, v37
	v_fmac_f32_e32 v39, v1, v36
	v_cndmask_b32_e32 v141, v38, v44, vcc
	v_fma_f32 v38, v0, v36, -v2
	v_mul_f32_e32 v41, v0, v39
	v_mul_f32_e32 v2, v1, v39
	v_fmac_f32_e32 v41, v1, v38
	v_fma_f32 v40, v0, v38, -v2
	v_mul_f32_e32 v43, v0, v41
	v_mul_f32_e32 v2, v1, v41
	v_fmac_f32_e32 v43, v1, v40
	v_fma_f32 v42, v0, v40, -v2
	v_mul_f32_e32 v45, v0, v43
	v_mul_f32_e32 v2, v1, v43
	v_fmac_f32_e32 v45, v1, v42
	v_cndmask_b32_e32 v115, v47, v48, vcc
	v_fma_f32 v44, v0, v42, -v2
	v_mul_f32_e32 v47, v0, v45
	v_mul_f32_e32 v2, v1, v45
	v_fmac_f32_e32 v47, v1, v44
	v_cndmask_b32_e32 v117, v46, v49, vcc
	v_fma_f32 v46, v0, v44, -v2
	v_mul_f32_e32 v49, v0, v47
	v_mul_f32_e32 v2, v1, v47
	v_fmac_f32_e32 v49, v1, v46
	v_cndmask_b32_e32 v99, v51, v59, vcc
	v_fma_f32 v48, v0, v46, -v2
	v_mul_f32_e32 v51, v0, v49
	v_mul_f32_e32 v2, v1, v49
	v_fmac_f32_e32 v51, v1, v48
	v_cndmask_b32_e32 v98, v50, v58, vcc
	v_fma_f32 v50, v0, v48, -v2
	v_mul_f32_e32 v2, v1, v51
	v_cndmask_b32_e32 v100, v52, v60, vcc
	v_fmac_f32_e32 v86, v3, v80
	v_fma_f32 v52, v0, v50, -v2
	v_lshl_add_u64 v[2:3], s[4:5], 0, v[122:123]
	v_lshl_add_u64 v[2:3], v[2:3], 0, v[120:121]
	v_cndmask_b32_e32 v104, v56, v80, vcc
	v_cndmask_b32_e32 v105, v57, v81, vcc
	s_mov_b64 s[98:99], s[4:5]
	s_add_i32 m0, s100, 0x0
	s_nop 0
	global_load_lds_dwordx4 v174, s[98:99]
	s_add_u32 s98, s98, 0x20000
	s_addc_u32 s99, s99, 0
	s_add_i32 m0, s100, 0x400
	s_nop 0
	global_load_lds_dwordx4 v174, s[98:99]
	s_add_u32 s98, s98, 0x20000
	s_addc_u32 s99, s99, 0
	s_add_i32 m0, s100, 0x800
	s_nop 0
	global_load_lds_dwordx4 v174, s[98:99]
	s_add_u32 s98, s98, 0x20000
	s_addc_u32 s99, s99, 0
	s_add_i32 m0, s100, 0xc00
	s_nop 0
	global_load_lds_dwordx4 v174, s[98:99]
	s_add_u32 s98, s98, 0x20000
	s_addc_u32 s99, s99, 0
	s_add_i32 m0, s100, 0x1000
	s_nop 0
	global_load_lds_dwordx4 v174, s[98:99]
	s_add_u32 s98, s98, 0x20000
	s_addc_u32 s99, s99, 0
	s_add_i32 m0, s100, 0x1400
	s_nop 0
	global_load_lds_dwordx4 v174, s[98:99]
	s_add_u32 s98, s98, 0x20000
	s_addc_u32 s99, s99, 0
	s_add_i32 m0, s100, 0x1800
	s_nop 0
	global_load_lds_dwordx4 v174, s[98:99]
	s_add_u32 s98, s98, 0x20000
	s_addc_u32 s99, s99, 0
	s_mov_b32 s101, 0
	v_cndmask_b32_e32 v101, v53, v61, vcc
	v_mul_f32_e32 v53, v0, v51
	v_fmac_f32_e32 v53, v1, v50
	v_mul_f32_e32 v3, v0, v53
	v_mul_f32_e32 v2, v1, v53
	v_fmac_f32_e32 v3, v1, v52
	v_cndmask_b32_e32 v103, v55, v63, vcc
	v_fma_f32 v2, v0, v52, -v2
	v_mul_f32_e32 v55, v0, v3
	v_cndmask_b32_e32 v102, v54, v62, vcc
	v_mul_f32_e32 v54, v1, v3
	v_fmac_f32_e32 v55, v1, v2
	v_fma_f32 v54, v0, v2, -v54
	v_mul_f32_e32 v57, v0, v55
	v_mul_f32_e32 v56, v1, v55
	v_fmac_f32_e32 v57, v1, v54
	v_fma_f32 v56, v0, v54, -v56
	v_mul_f32_e32 v59, v0, v57
	v_mul_f32_e32 v58, v1, v57
	v_fmac_f32_e32 v59, v1, v56
	v_fma_f32 v58, v0, v56, -v58
	v_mul_f32_e32 v61, v0, v59
	v_mul_f32_e32 v60, v1, v59
	v_fmac_f32_e32 v61, v1, v58
	v_fma_f32 v60, v0, v58, -v60
	v_mul_f32_e32 v63, v0, v61
	v_mul_f32_e32 v62, v1, v61
	v_fmac_f32_e32 v63, v1, v60
	v_fma_f32 v62, v0, v60, -v62
	v_mul_f32_e32 v85, v1, v63
	v_fma_f32 v90, v0, v62, -v85
	v_mul_f32_e32 v92, v0, v63
	v_lshl_or_b32 v0, v134, 12, s9
	v_readlane_b32 s9, v253, 8
	s_add_i32 s8, s9, s8
	s_and_b32 s8, s8, 0x7f
	s_lshl_b32 s8, s8, 5
	v_fmac_f32_e32 v92, v1, v62
	v_or3_b32 v0, v0, s8, v135
	v_mov_b32_e32 v1, s3
	v_lshl_add_u64 v[0:1], s[82:83], 0, v[0:1]
	s_mov_b64 s[8:9], 0xa820000
	v_cndmask_b32_e32 v170, v54, v62, vcc
	v_cndmask_b32_e32 v171, v55, v63, vcc
	v_cndmask_b32_e32 v168, v2, v60, vcc
	v_cndmask_b32_e32 v169, v3, v61, vcc
	v_cndmask_b32_e32 v166, v52, v58, vcc
	v_cndmask_b32_e32 v167, v53, v59, vcc
	v_cndmask_b32_e32 v164, v50, v56, vcc
	v_cndmask_b32_e32 v165, v51, v57, vcc
	v_cndmask_b32_e32 v162, v40, v48, vcc
	v_cndmask_b32_e32 v163, v41, v49, vcc
	v_cndmask_b32_e32 v160, v38, v46, vcc
	v_cndmask_b32_e32 v161, v39, v47, vcc
	v_cndmask_b32_e32 v158, v36, v44, vcc
	v_cndmask_b32_e32 v159, v37, v45, vcc
	v_cndmask_b32_e32 v156, v34, v42, vcc
	v_cndmask_b32_e32 v157, v35, v43, vcc
	v_cndmask_b32_e32 v154, v24, v32, vcc
	v_cndmask_b32_e32 v155, v25, v33, vcc
	v_cndmask_b32_e32 v152, v22, v30, vcc
	v_cndmask_b32_e32 v153, v23, v31, vcc
	v_cndmask_b32_e32 v150, v20, v28, vcc
	v_cndmask_b32_e32 v151, v21, v29, vcc
	v_cndmask_b32_e32 v148, v18, v26, vcc
	v_cndmask_b32_e32 v149, v19, v27, vcc
	v_cndmask_b32_e32 v146, v8, v16, vcc
	v_cndmask_b32_e32 v147, v9, v17, vcc
	v_cndmask_b32_e32 v144, v6, v14, vcc
	v_cndmask_b32_e32 v145, v7, v15, vcc
	v_cndmask_b32_e32 v142, v4, v12, vcc
	v_cndmask_b32_e32 v143, v5, v13, vcc
	v_cndmask_b32_e32 v121, 1.0, v10, vcc
	v_cndmask_b32_e32 v123, 0, v11, vcc
	v_xor_b32_e32 v87, 0x80000000, v86
	v_xor_b32_e32 v93, 0x80000000, v92
	v_mov_b32_e32 v89, v88
	v_mov_b32_e32 v91, v90
	v_lshl_add_u64 v[96:97], v[0:1], 0, s[8:9]
	s_mov_b64 s[8:9], 0
	v_mov_b32_e32 v85, v84
	v_mov_b32_e32 v180, v104
	v_mov_b32_e32 v181, v102
	v_mov_b32_e32 v214, v105
	v_mov_b32_e32 v215, v103
	v_mov_b32_e32 v182, v100
	v_mov_b32_e32 v183, v98
	v_mov_b32_e32 v216, v101
	v_mov_b32_e32 v217, v99
	v_mov_b32_e32 v184, v115
	v_mov_b32_e32 v185, v140
	v_mov_b32_e32 v218, v117
	v_mov_b32_e32 v219, v141
	v_mov_b32_e32 v186, v138
	v_mov_b32_e32 v187, v136
	v_mov_b32_e32 v220, v139
	v_mov_b32_e32 v221, v137
	v_mov_b32_e32 v188, v131
	v_mov_b32_e32 v189, v129
	v_mov_b32_e32 v222, v133
	v_mov_b32_e32 v223, v130
	v_mov_b32_e32 v190, v118
	v_mov_b32_e32 v191, v114
	v_mov_b32_e32 v224, v119
	v_mov_b32_e32 v225, v116
	v_mov_b32_e32 v192, v112
	v_mov_b32_e32 v193, v110
	v_mov_b32_e32 v226, v113
	v_mov_b32_e32 v227, v111
	v_mov_b32_e32 v194, v108
	v_mov_b32_e32 v195, v106
	v_mov_b32_e32 v228, v109
	v_mov_b32_e32 v229, v107
	v_mov_b32_e32 v196, v170
	v_mov_b32_e32 v197, v168
	v_mov_b32_e32 v230, v171
	v_mov_b32_e32 v231, v169
	v_mov_b32_e32 v198, v166
	v_mov_b32_e32 v199, v164
	v_mov_b32_e32 v232, v167
	v_mov_b32_e32 v233, v165
	v_mov_b32_e32 v200, v162
	v_mov_b32_e32 v201, v160
	v_mov_b32_e32 v234, v163
	v_mov_b32_e32 v235, v161
	v_mov_b32_e32 v202, v158
	v_mov_b32_e32 v203, v156
	v_mov_b32_e32 v236, v159
	v_mov_b32_e32 v237, v157
	v_mov_b32_e32 v204, v154
	v_mov_b32_e32 v205, v152
	v_mov_b32_e32 v238, v155
	v_mov_b32_e32 v239, v153
	v_mov_b32_e32 v206, v150
	v_mov_b32_e32 v207, v148
	v_mov_b32_e32 v240, v151
	v_mov_b32_e32 v241, v149
	v_mov_b32_e32 v210, v146
	v_mov_b32_e32 v211, v144
	v_mov_b32_e32 v242, v147
	v_mov_b32_e32 v243, v145
	v_mov_b32_e32 v212, v142
	v_mov_b32_e32 v213, v121
	v_mov_b32_e32 v244, v143
	v_mov_b32_e32 v245, v123
.LBB0_898:
	s_waitcnt vmcnt(6)
	v_add_u32_e32 v177, s101, v175
	ds_read_b128 v[16:19], v177
	s_add_i32 s8, s101, 0x1c00
	s_and_b32 s8, s8, 0x1c00
	s_add_i32 m0, s100, s8
	s_cmp_lt_u32 s9, 8
	global_load_lds_dwordx4 v174, s[98:99]
	s_cselect_b32 s8, 0x20000, 0
	s_add_u32 s98, s98, s8
	s_addc_u32 s99, s99, 0
	s_add_i32 s101, s101, 0x400
	s_and_b32 s101, s101, 0x1c00
	s_add_i32 s9, s9, 1
	s_waitcnt lgkmcnt(0)
	v_mfma_f32_32x32x16_bf16 v[32:47], v[16:19], v[64:67], 0
	s_cmp_lg_u32 s9, 16
	v_mfma_f32_32x32x16_bf16 v[48:63], v[16:19], v[72:75], 0
	v_mfma_f32_32x32x16_bf16 v[0:15], v[16:19], v[68:71], 0
	v_mfma_f32_32x32x16_bf16 v[16:31], v[16:19], v[76:79], 0
	s_nop 9
	v_pk_mul_f32 v[172:173], v[180:181], v[32:33]
	v_pk_mul_f32 v[32:33], v[214:215], v[32:33]
	v_pk_fma_f32 v[172:173], v[214:215], v[48:49], v[172:173] neg_lo:[1,0,0] neg_hi:[1,0,0]
	v_pk_fma_f32 v[32:33], v[180:181], v[48:49], v[32:33]
	v_pk_fma_f32 v[172:173], v[182:183], v[34:35], v[172:173]
	v_pk_fma_f32 v[32:33], v[216:217], v[34:35], v[32:33]
	v_pk_fma_f32 v[172:173], v[216:217], v[50:51], v[172:173] neg_lo:[1,0,0] neg_hi:[1,0,0]
	v_pk_fma_f32 v[32:33], v[182:183], v[50:51], v[32:33]
	v_pk_fma_f32 v[172:173], v[184:185], v[36:37], v[172:173]
	v_pk_fma_f32 v[32:33], v[218:219], v[36:37], v[32:33]
	v_pk_fma_f32 v[172:173], v[218:219], v[52:53], v[172:173] neg_lo:[1,0,0] neg_hi:[1,0,0]
	v_pk_fma_f32 v[32:33], v[184:185], v[52:53], v[32:33]
	v_pk_fma_f32 v[172:173], v[186:187], v[38:39], v[172:173]
	v_pk_fma_f32 v[32:33], v[220:221], v[38:39], v[32:33]
	v_pk_fma_f32 v[172:173], v[220:221], v[54:55], v[172:173] neg_lo:[1,0,0] neg_hi:[1,0,0]
	v_pk_fma_f32 v[32:33], v[186:187], v[54:55], v[32:33]
	v_pk_fma_f32 v[172:173], v[188:189], v[40:41], v[172:173]
	v_pk_fma_f32 v[32:33], v[222:223], v[40:41], v[32:33]
	v_pk_fma_f32 v[172:173], v[222:223], v[56:57], v[172:173] neg_lo:[1,0,0] neg_hi:[1,0,0]
	v_pk_fma_f32 v[32:33], v[188:189], v[56:57], v[32:33]
	v_pk_fma_f32 v[172:173], v[190:191], v[42:43], v[172:173]
	v_pk_fma_f32 v[32:33], v[224:225], v[42:43], v[32:33]
	v_pk_fma_f32 v[172:173], v[224:225], v[58:59], v[172:173] neg_lo:[1,0,0] neg_hi:[1,0,0]
	v_pk_fma_f32 v[32:33], v[190:191], v[58:59], v[32:33]
	v_pk_fma_f32 v[172:173], v[192:193], v[44:45], v[172:173]
	v_pk_fma_f32 v[32:33], v[226:227], v[44:45], v[32:33]
	v_pk_fma_f32 v[172:173], v[226:227], v[60:61], v[172:173] neg_lo:[1,0,0] neg_hi:[1,0,0]
	v_pk_fma_f32 v[32:33], v[192:193], v[60:61], v[32:33]
	v_pk_fma_f32 v[172:173], v[194:195], v[46:47], v[172:173]
	v_pk_fma_f32 v[32:33], v[228:229], v[46:47], v[32:33]
	v_pk_fma_f32 v[172:173], v[228:229], v[62:63], v[172:173] neg_lo:[1,0,0] neg_hi:[1,0,0]
	v_pk_fma_f32 v[32:33], v[194:195], v[62:63], v[32:33]
	v_pk_mul_f32 v[48:49], v[196:197], v[0:1]
	v_pk_mul_f32 v[0:1], v[230:231], v[0:1]
	v_pk_fma_f32 v[48:49], v[230:231], v[16:17], v[48:49] neg_lo:[1,0,0] neg_hi:[1,0,0]
	v_pk_fma_f32 v[0:1], v[196:197], v[16:17], v[0:1]
	v_pk_fma_f32 v[48:49], v[198:199], v[2:3], v[48:49]
	v_pk_fma_f32 v[0:1], v[232:233], v[2:3], v[0:1]
	v_pk_fma_f32 v[48:49], v[232:233], v[18:19], v[48:49] neg_lo:[1,0,0] neg_hi:[1,0,0]
	v_pk_fma_f32 v[0:1], v[198:199], v[18:19], v[0:1]
	v_pk_fma_f32 v[48:49], v[200:201], v[4:5], v[48:49]
	v_pk_fma_f32 v[0:1], v[234:235], v[4:5], v[0:1]
	v_pk_fma_f32 v[48:49], v[234:235], v[20:21], v[48:49] neg_lo:[1,0,0] neg_hi:[1,0,0]
	v_pk_fma_f32 v[0:1], v[200:201], v[20:21], v[0:1]
	v_pk_fma_f32 v[48:49], v[202:203], v[6:7], v[48:49]
	v_pk_fma_f32 v[0:1], v[236:237], v[6:7], v[0:1]
	v_pk_fma_f32 v[48:49], v[236:237], v[22:23], v[48:49] neg_lo:[1,0,0] neg_hi:[1,0,0]
	v_pk_fma_f32 v[0:1], v[202:203], v[22:23], v[0:1]
	v_pk_fma_f32 v[48:49], v[204:205], v[8:9], v[48:49]
	v_pk_fma_f32 v[0:1], v[238:239], v[8:9], v[0:1]
	v_pk_fma_f32 v[48:49], v[238:239], v[24:25], v[48:49] neg_lo:[1,0,0] neg_hi:[1,0,0]
	v_pk_fma_f32 v[0:1], v[204:205], v[24:25], v[0:1]
	v_pk_fma_f32 v[48:49], v[206:207], v[10:11], v[48:49]
	v_pk_fma_f32 v[0:1], v[240:241], v[10:11], v[0:1]
	v_pk_fma_f32 v[48:49], v[240:241], v[26:27], v[48:49] neg_lo:[1,0,0] neg_hi:[1,0,0]
	v_pk_fma_f32 v[0:1], v[206:207], v[26:27], v[0:1]
	v_pk_fma_f32 v[48:49], v[210:211], v[12:13], v[48:49]
	v_pk_fma_f32 v[0:1], v[242:243], v[12:13], v[0:1]
	v_pk_fma_f32 v[48:49], v[242:243], v[28:29], v[48:49] neg_lo:[1,0,0] neg_hi:[1,0,0]
	v_pk_fma_f32 v[0:1], v[210:211], v[28:29], v[0:1]
	v_pk_fma_f32 v[48:49], v[212:213], v[14:15], v[48:49]
	v_pk_fma_f32 v[0:1], v[244:245], v[14:15], v[0:1]
	v_pk_fma_f32 v[48:49], v[244:245], v[30:31], v[48:49] neg_lo:[1,0,0] neg_hi:[1,0,0]
	v_pk_fma_f32 v[0:1], v[212:213], v[30:31], v[0:1]
	v_add_f32_e32 v32, v32, v33
	v_add_f32_e32 v33, v172, v173
	v_add_f32_e32 v0, v0, v1
	v_add_f32_e32 v1, v48, v49
	v_mov_b32_e32 v35, v33
	v_mov_b32_e32 v34, v32
	v_mov_b32_e32 v3, v1
	v_mov_b32_e32 v2, v0
	v_permlane32_swap_b32_e32 v33, v35
	v_permlane32_swap_b32_e32 v32, v34
	v_permlane32_swap_b32_e32 v1, v3
	v_permlane32_swap_b32_e32 v0, v2
	v_pk_add_f32 v[4:5], v[32:33], v[34:35]
	v_pk_add_f32 v[0:1], v[0:1], v[2:3]
	v_pk_fma_f32 v[4:5], v[86:87], v[84:85], v[4:5] op_sel:[0,1,0] op_sel_hi:[1,0,1]
	v_pk_fma_f32 v[0:1], v[92:93], v[94:95], v[0:1] op_sel:[0,1,0] op_sel_hi:[1,0,1]
	v_pk_fma_f32 v[84:85], v[88:89], v[84:85], v[4:5]
	v_pk_fma_f32 v[94:95], v[90:91], v[94:95], v[0:1]
	s_cbranch_scc1 .LBB0_898
	v_cmp_gt_u32_e32 vcc, 32, v128
	s_nop 1
	v_cndmask_b32_e32 v0, v95, v85, vcc
	v_cndmask_b32_e32 v1, v94, v84, vcc
